# LRU pass1: conv taps masked on packed inputs under uniform test, packed-f32 gate math with double-buffered table reads
# speedup vs baseline: 1.0275x; 1.0088x over previous
.LBB0_339:
	ds_read_b128 v[2:5], v187
	ds_read_b128 v[6:9], v187 offset:16
	ds_read_b128 v[14:17], v189
	ds_read_b128 v[10:13], v189 offset:16
	ds_read_b128 v[144:147], v188
	ds_read_b128 v[148:151], v188 offset:16
	ds_read_b128 v[152:155], v196
	ds_read_b128 v[156:159], v196 offset:16
	ds_read_b128 v[160:163], v188 offset:2048
	ds_read_b128 v[164:167], v188 offset:2064
	ds_read_b128 v[130:133], v196 offset:2048
	ds_read_b128 v[134:137], v196 offset:2064
	s_mov_b32 s40, s37
	v_add_u32_e32 v0, s40, v186
	v_cmp_lt_i32_e32 vcc, 1, v0
	v_cmp_gt_i32_e64 s[10:11], s48, v0
	s_and_b64 s[14:15], vcc, s[10:11]
	v_cmp_lt_i32_e32 vcc, 0, v0
	v_cmp_ge_i32_e64 s[10:11], s3, v0
	s_and_b64 s[10:11], vcc, s[10:11]
	v_cmp_gt_i32_e32 vcc, s3, v0
	s_and_b64 s[12:13], s[38:39], vcc
	v_cmp_lt_i32_e32 vcc, -2, v0
	v_cmp_gt_i32_e64 s[16:17], s49, v0
	s_and_b64 vcc, vcc, s[16:17]
	s_and_b64 s[16:17], s[14:15], s[10:11]
	s_and_b64 s[16:17], s[16:17], s[12:13]
	s_and_b64 s[16:17], s[16:17], vcc
	s_cmp_eq_u64 s[16:17], exec
	s_waitcnt vmcnt(0)
	s_cbranch_scc1 .Lconv_nomask
	v_cndmask_b32_e64 v126, 0, v126, s[14:15]
	v_cndmask_b32_e64 v127, 0, v127, s[14:15]
	v_cndmask_b32_e64 v128, 0, v128, s[14:15]
	v_cndmask_b32_e64 v129, 0, v129, s[14:15]
	v_cndmask_b32_e64 v110, 0, v110, s[14:15]
	v_cndmask_b32_e64 v111, 0, v111, s[14:15]
	v_cndmask_b32_e64 v112, 0, v112, s[14:15]
	v_cndmask_b32_e64 v113, 0, v113, s[14:15]
	v_cndmask_b32_e64 v122, 0, v122, s[10:11]
	v_cndmask_b32_e64 v123, 0, v123, s[10:11]
	v_cndmask_b32_e64 v124, 0, v124, s[10:11]
	v_cndmask_b32_e64 v125, 0, v125, s[10:11]
	v_cndmask_b32_e64 v106, 0, v106, s[10:11]
	v_cndmask_b32_e64 v107, 0, v107, s[10:11]
	v_cndmask_b32_e64 v108, 0, v108, s[10:11]
	v_cndmask_b32_e64 v109, 0, v109, s[10:11]
	v_cndmask_b32_e64 v118, 0, v118, s[12:13]
	v_cndmask_b32_e64 v119, 0, v119, s[12:13]
	v_cndmask_b32_e64 v120, 0, v120, s[12:13]
	v_cndmask_b32_e64 v121, 0, v121, s[12:13]
	v_cndmask_b32_e64 v102, 0, v102, s[12:13]
	v_cndmask_b32_e64 v103, 0, v103, s[12:13]
	v_cndmask_b32_e64 v104, 0, v104, s[12:13]
	v_cndmask_b32_e64 v105, 0, v105, s[12:13]
	v_cndmask_b32_e32 v114, 0, v114, vcc
	v_cndmask_b32_e32 v115, 0, v115, vcc
	v_cndmask_b32_e32 v116, 0, v116, vcc
	v_cndmask_b32_e32 v117, 0, v117, vcc
	v_cndmask_b32_e32 v98, 0, v98, vcc
	v_cndmask_b32_e32 v99, 0, v99, vcc
	v_cndmask_b32_e32 v100, 0, v100, vcc
	v_cndmask_b32_e32 v101, 0, v101, vcc
.Lconv_nomask:
	v_lshlrev_b32_e32 v18, 16, v126
	v_and_b32_e32 v19, 0xffff0000, v126
	v_lshlrev_b32_e32 v20, 16, v127
	v_and_b32_e32 v21, 0xffff0000, v127
	v_lshlrev_b32_e32 v22, 16, v128
	v_and_b32_e32 v23, 0xffff0000, v128
	v_lshlrev_b32_e32 v24, 16, v129
	v_and_b32_e32 v25, 0xffff0000, v129
	v_lshlrev_b32_e32 v26, 16, v110
	v_and_b32_e32 v27, 0xffff0000, v110
	v_lshlrev_b32_e32 v28, 16, v111
	v_and_b32_e32 v29, 0xffff0000, v111
	v_lshlrev_b32_e32 v30, 16, v112
	v_and_b32_e32 v31, 0xffff0000, v112
	v_lshlrev_b32_e32 v32, 16, v113
	v_and_b32_e32 v33, 0xffff0000, v113
	s_waitcnt lgkmcnt(4)
	v_pk_fma_f32 v[2:3], v[144:145], v[18:19], v[2:3]
	v_pk_fma_f32 v[4:5], v[146:147], v[20:21], v[4:5]
	v_pk_fma_f32 v[6:7], v[148:149], v[22:23], v[6:7]
	v_pk_fma_f32 v[8:9], v[150:151], v[24:25], v[8:9]
	v_pk_fma_f32 v[14:15], v[152:153], v[26:27], v[14:15]
	v_pk_fma_f32 v[16:17], v[154:155], v[28:29], v[16:17]
	v_pk_fma_f32 v[10:11], v[156:157], v[30:31], v[10:11]
	v_pk_fma_f32 v[12:13], v[158:159], v[32:33], v[12:13]
	ds_read_b128 v[144:147], v188 offset:4096
	ds_read_b128 v[148:151], v188 offset:4112
	ds_read_b128 v[152:155], v196 offset:4096
	ds_read_b128 v[156:159], v196 offset:4112
	v_lshlrev_b32_e32 v18, 16, v122
	v_and_b32_e32 v19, 0xffff0000, v122
	v_lshlrev_b32_e32 v20, 16, v123
	v_and_b32_e32 v21, 0xffff0000, v123
	v_lshlrev_b32_e32 v22, 16, v124
	v_and_b32_e32 v23, 0xffff0000, v124
	v_lshlrev_b32_e32 v24, 16, v125
	v_and_b32_e32 v25, 0xffff0000, v125
	v_lshlrev_b32_e32 v26, 16, v106
	v_and_b32_e32 v27, 0xffff0000, v106
	v_lshlrev_b32_e32 v28, 16, v107
	v_and_b32_e32 v29, 0xffff0000, v107
	v_lshlrev_b32_e32 v30, 16, v108
	v_and_b32_e32 v31, 0xffff0000, v108
	v_lshlrev_b32_e32 v32, 16, v109
	v_and_b32_e32 v33, 0xffff0000, v109
	s_waitcnt lgkmcnt(4)
	v_pk_fma_f32 v[2:3], v[160:161], v[18:19], v[2:3]
	v_pk_fma_f32 v[4:5], v[162:163], v[20:21], v[4:5]
	v_pk_fma_f32 v[6:7], v[164:165], v[22:23], v[6:7]
	v_pk_fma_f32 v[8:9], v[166:167], v[24:25], v[8:9]
	v_pk_fma_f32 v[14:15], v[130:131], v[26:27], v[14:15]
	v_pk_fma_f32 v[16:17], v[132:133], v[28:29], v[16:17]
	v_pk_fma_f32 v[10:11], v[134:135], v[30:31], v[10:11]
	v_pk_fma_f32 v[12:13], v[136:137], v[32:33], v[12:13]
	ds_read_b128 v[160:163], v188 offset:6144
	ds_read_b128 v[164:167], v188 offset:6160
	ds_read_b128 v[130:133], v196 offset:6144
	ds_read_b128 v[134:137], v196 offset:6160
	v_lshlrev_b32_e32 v18, 16, v118
	v_and_b32_e32 v19, 0xffff0000, v118
	v_lshlrev_b32_e32 v20, 16, v119
	v_and_b32_e32 v21, 0xffff0000, v119
	v_lshlrev_b32_e32 v22, 16, v120
	v_and_b32_e32 v23, 0xffff0000, v120
	v_lshlrev_b32_e32 v24, 16, v121
	v_and_b32_e32 v25, 0xffff0000, v121
	v_lshlrev_b32_e32 v26, 16, v102
	v_and_b32_e32 v27, 0xffff0000, v102
	v_lshlrev_b32_e32 v28, 16, v103
	v_and_b32_e32 v29, 0xffff0000, v103
	v_lshlrev_b32_e32 v30, 16, v104
	v_and_b32_e32 v31, 0xffff0000, v104
	v_lshlrev_b32_e32 v32, 16, v105
	v_and_b32_e32 v33, 0xffff0000, v105
	s_waitcnt lgkmcnt(4)
	v_pk_fma_f32 v[2:3], v[144:145], v[18:19], v[2:3]
	v_pk_fma_f32 v[4:5], v[146:147], v[20:21], v[4:5]
	v_pk_fma_f32 v[6:7], v[148:149], v[22:23], v[6:7]
	v_pk_fma_f32 v[8:9], v[150:151], v[24:25], v[8:9]
	v_pk_fma_f32 v[14:15], v[152:153], v[26:27], v[14:15]
	v_pk_fma_f32 v[16:17], v[154:155], v[28:29], v[16:17]
	v_pk_fma_f32 v[10:11], v[156:157], v[30:31], v[10:11]
	v_pk_fma_f32 v[12:13], v[158:159], v[32:33], v[12:13]
	v_lshlrev_b32_e32 v18, 16, v114
	v_and_b32_e32 v19, 0xffff0000, v114
	v_lshlrev_b32_e32 v20, 16, v115
	v_and_b32_e32 v21, 0xffff0000, v115
	v_lshlrev_b32_e32 v22, 16, v116
	v_and_b32_e32 v23, 0xffff0000, v116
	v_lshlrev_b32_e32 v24, 16, v117
	v_and_b32_e32 v25, 0xffff0000, v117
	v_lshlrev_b32_e32 v26, 16, v98
	v_and_b32_e32 v27, 0xffff0000, v98
	v_lshlrev_b32_e32 v28, 16, v99
	v_and_b32_e32 v29, 0xffff0000, v99
	v_lshlrev_b32_e32 v30, 16, v100
	v_and_b32_e32 v31, 0xffff0000, v100
	v_lshlrev_b32_e32 v32, 16, v101
	v_and_b32_e32 v33, 0xffff0000, v101
	s_waitcnt lgkmcnt(0)
	v_pk_fma_f32 v[2:3], v[160:161], v[18:19], v[2:3]
	v_pk_fma_f32 v[4:5], v[162:163], v[20:21], v[4:5]
	v_pk_fma_f32 v[6:7], v[164:165], v[22:23], v[6:7]
	v_pk_fma_f32 v[8:9], v[166:167], v[24:25], v[8:9]
	v_pk_fma_f32 v[14:15], v[130:131], v[26:27], v[14:15]
	v_pk_fma_f32 v[16:17], v[132:133], v[28:29], v[16:17]
	v_pk_fma_f32 v[10:11], v[134:135], v[30:31], v[10:11]
	v_pk_fma_f32 v[12:13], v[136:137], v[32:33], v[12:13]
	v_cvt_pk_bf16_f32 v134, v2, v3
	v_cvt_pk_bf16_f32 v135, v4, v5
	v_cvt_pk_bf16_f32 v136, v6, v7
	ds_write_b128 v212, v[2:5]
	ds_write_b128 v212, v[6:9] offset:16
	ds_write_b128 v212, v[14:17] offset:128
	ds_write_b128 v212, v[10:13] offset:144
	s_waitcnt lgkmcnt(0)
	v_cvt_pk_bf16_f32 v6, v14, v15
	v_cvt_pk_bf16_f32 v7, v16, v17
	ds_read_b128 v[150:153], v213
	ds_read_b128 v[26:29], v213 offset:64
	ds_read_b128 v[14:17], v213 offset:128
	ds_read_b128 v[2:5], v213 offset:192
	s_waitcnt lgkmcnt(0)
	v_cvt_pk_bf16_f32 v137, v8, v9
	v_cvt_pk_bf16_f32 v8, v10, v11
	v_cvt_pk_bf16_f32 v9, v12, v13
	s_add_i32 s37, s37, 16
	s_cmp_lg_u32 s40, 48
	s_cselect_b32 s10, s37, 48
	v_or_b32_e32 v20, s10, v184
	v_add_u32_e32 v21, s33, v20
	v_cmp_lt_i32_e32 vcc, 1, v21
	v_cmp_gt_i32_e64 s[10:11], s48, v21
	v_add_u32_e32 v0, -2, v20
	s_and_b64 vcc, vcc, s[10:11]
	v_cndmask_b32_e32 v10, v20, v0, vcc
	v_cmp_lt_i32_e32 vcc, 0, v21
	v_cmp_ge_i32_e64 s[10:11], s3, v21
	s_and_b64 vcc, vcc, s[10:11]
	v_subbrev_co_u32_e32 v12, vcc, 0, v20, vcc
	v_cmp_lt_i32_e32 vcc, -2, v21
	v_cmp_gt_i32_e64 s[10:11], s49, v21
	v_ashrrev_i32_e32 v11, 31, v10
	v_lshlrev_b32_e32 v0, 10, v20
	s_and_b64 vcc, vcc, s[10:11]
	v_lshlrev_b64 v[10:11], 10, v[10:11]
	v_ashrrev_i32_e32 v13, 31, v12
	v_lshl_add_u64 v[18:19], v[140:141], 0, v[0:1]
	v_addc_co_u32_e32 v0, vcc, 0, v20, vcc
	v_lshl_add_u64 v[10:11], v[140:141], 0, v[10:11]
	v_lshlrev_b64 v[12:13], 10, v[12:13]
	v_lshlrev_b32_e32 v0, 10, v0
	v_lshl_add_u64 v[12:13], v[140:141], 0, v[12:13]
	v_lshl_add_u64 v[20:21], v[140:141], 0, v[0:1]
	global_load_dwordx4 v[126:129], v[10:11], off
	global_load_dwordx4 v[110:113], v[10:11], off offset:64
	global_load_dwordx4 v[122:125], v[12:13], off
	global_load_dwordx4 v[106:109], v[12:13], off offset:64
	global_load_dwordx4 v[118:121], v[18:19], off
	global_load_dwordx4 v[102:105], v[18:19], off offset:64
	global_load_dwordx4 v[114:117], v[20:21], off
	global_load_dwordx4 v[98:101], v[20:21], off offset:64
	ds_read_b128 v[158:161], v197
	ds_read_b128 v[162:165], v198
	ds_read_b128 v[166:169], v199
	v_mfma_f32_16x16x32_bf16 v[10:13], v[34:37], v[134:137], 0
	s_mov_b64 s[10:11], -1
	v_mfma_f32_16x16x32_bf16 v[18:21], v[42:45], v[134:137], 0
	v_mfma_f32_16x16x32_bf16 v[146:149], v[38:41], v[6:9], v[10:13]
	v_mfma_f32_16x16x32_bf16 v[10:13], v[50:53], v[134:137], 0
	v_mfma_f32_16x16x32_bf16 v[154:157], v[46:49], v[6:9], v[18:21]
	v_mfma_f32_16x16x32_bf16 v[18:21], v[58:61], v[134:137], 0
	v_mfma_f32_16x16x32_bf16 v[130:133], v[54:57], v[6:9], v[10:13]
	v_mfma_f32_16x16x32_bf16 v[10:13], v[66:69], v[134:137], 0
	v_mfma_f32_16x16x32_bf16 v[30:33], v[62:65], v[6:9], v[18:21]
	v_mfma_f32_16x16x32_bf16 v[18:21], v[70:73], v[134:137], 0
	v_mfma_f32_16x16x32_bf16 v[22:25], v[74:77], v[6:9], v[10:13]
	v_mfma_f32_16x16x32_bf16 v[10:13], v[82:85], v[134:137], 0
	v_mfma_f32_16x16x32_bf16 v[134:137], v[86:89], v[134:137], 0
	v_mfma_f32_16x16x32_bf16 v[18:21], v[78:81], v[6:9], v[18:21]
	v_mfma_f32_16x16x32_bf16 v[10:13], v[90:93], v[6:9], v[10:13]
	v_mfma_f32_16x16x32_bf16 v[6:9], v[94:97], v[6:9], v[134:137]
	s_nop 4
	ds_read_b128 v[246:249], v202
	ds_read_b128 v[250:253], v203
	ds_read_b128 v[134:137], v204
	v_mov_b32_e32 v170, 0xbfb8aa3b
	v_mov_b32_e32 v226, 0x3fb17218
	s_waitcnt lgkmcnt(3)
	v_pk_add_f32 v[146:147], v[146:147], v[158:159]
	v_pk_add_f32 v[148:149], v[148:149], v[160:161]
	v_pk_add_f32 v[154:155], v[154:155], v[162:163]
	v_pk_add_f32 v[156:157], v[156:157], v[164:165]
	v_pk_mul_f32 v[146:147], v[146:147], v[170:171] op_sel_hi:[1,0]
	v_pk_mul_f32 v[148:149], v[148:149], v[170:171] op_sel_hi:[1,0]
	v_pk_mul_f32 v[154:155], v[154:155], v[170:171] op_sel_hi:[1,0]
	v_pk_mul_f32 v[156:157], v[156:157], v[170:171] op_sel_hi:[1,0]
	v_exp_f32_e32 v146, v146
	v_exp_f32_e32 v147, v147
	v_exp_f32_e32 v148, v148
	v_exp_f32_e32 v149, v149
	v_exp_f32_e32 v154, v154
	v_exp_f32_e32 v155, v155
	v_exp_f32_e32 v156, v156
	v_exp_f32_e32 v157, v157
	v_pk_add_f32 v[146:147], v[146:147], 1.0 op_sel_hi:[1,0]
	v_pk_add_f32 v[148:149], v[148:149], 1.0 op_sel_hi:[1,0]
	v_pk_add_f32 v[154:155], v[154:155], 1.0 op_sel_hi:[1,0]
	v_pk_add_f32 v[156:157], v[156:157], 1.0 op_sel_hi:[1,0]
	v_rcp_f32_e32 v146, v146
	v_rcp_f32_e32 v147, v147
	v_rcp_f32_e32 v148, v148
	v_rcp_f32_e32 v149, v149
	v_rcp_f32_e32 v154, v154
	v_rcp_f32_e32 v155, v155
	v_rcp_f32_e32 v156, v156
	v_rcp_f32_e32 v157, v157
	v_pk_mul_f32 v[166:167], v[166:167], v[146:147]
	v_pk_mul_f32 v[168:169], v[168:169], v[148:149]
	v_exp_f32_e32 v146, v166
	v_exp_f32_e32 v147, v167
	v_exp_f32_e32 v148, v168
	v_exp_f32_e32 v149, v169
	v_pk_mul_f32 v[158:159], v[166:167], v[226:227] op_sel_hi:[1,0]
	v_pk_mul_f32 v[160:161], v[168:169], v[226:227] op_sel_hi:[1,0]
	v_pk_fma_f32 v[162:163], v[158:159], 0.5, 1.0 op_sel_hi:[1,0,0]
	v_pk_fma_f32 v[164:165], v[160:161], 0.5, 1.0 op_sel_hi:[1,0,0]
	v_pk_mul_f32 v[162:163], v[162:163], v[158:159] neg_lo:[0,1] neg_hi:[0,1]
	v_pk_mul_f32 v[164:165], v[164:165], v[160:161] neg_lo:[0,1] neg_hi:[0,1]
	v_cmp_lt_f32_e32 vcc, s72, v158
	v_cmp_lt_f32_e64 s[12:13], s72, v159
	v_cmp_lt_f32_e64 s[14:15], s72, v160
	v_cmp_lt_f32_e64 s[16:17], s72, v161
	v_pk_fma_f32 v[158:159], v[146:147], v[146:147], 1.0 op_sel_hi:[1,1,0] neg_lo:[1,0,0] neg_hi:[1,0,0]
	v_pk_fma_f32 v[160:161], v[148:149], v[148:149], 1.0 op_sel_hi:[1,1,0] neg_lo:[1,0,0] neg_hi:[1,0,0]
	v_cndmask_b32_e32 v158, v158, v162, vcc
	v_cndmask_b32_e64 v159, v159, v163, s[12:13]
	v_cndmask_b32_e64 v160, v160, v164, s[14:15]
	v_cndmask_b32_e64 v161, v161, v165, s[16:17]
	v_sqrt_f32_e32 v158, v158
	v_sqrt_f32_e32 v159, v159
	v_sqrt_f32_e32 v160, v160
	v_sqrt_f32_e32 v161, v161
	v_pk_mul_f32 v[154:155], v[154:155], v[158:159]
	v_pk_mul_f32 v[156:157], v[156:157], v[160:161]
	v_pk_mul_f32 v[150:151], v[150:151], v[154:155]
	v_pk_mul_f32 v[152:153], v[152:153], v[156:157]
	v_cvt_pkrtz_f16_f32 v162, v166, v150
	v_cvt_pkrtz_f16_f32 v163, v167, v151
	v_cvt_pkrtz_f16_f32 v164, v168, v152
	v_cvt_pkrtz_f16_f32 v165, v169, v153
	global_store_dwordx4 v[142:143], v[162:165], off offset:-2048
	ds_read_b128 v[158:161], v205
	ds_read_b128 v[162:165], v206
	ds_read_b128 v[166:169], v207
	s_waitcnt lgkmcnt(3)
	v_pk_add_f32 v[130:131], v[130:131], v[246:247]
	v_pk_add_f32 v[132:133], v[132:133], v[248:249]
	v_pk_add_f32 v[30:31], v[30:31], v[250:251]
	v_pk_add_f32 v[32:33], v[32:33], v[252:253]
	v_pk_mul_f32 v[130:131], v[130:131], v[170:171] op_sel_hi:[1,0]
	v_pk_mul_f32 v[132:133], v[132:133], v[170:171] op_sel_hi:[1,0]
	v_pk_mul_f32 v[30:31], v[30:31], v[170:171] op_sel_hi:[1,0]
	v_pk_mul_f32 v[32:33], v[32:33], v[170:171] op_sel_hi:[1,0]
	v_exp_f32_e32 v130, v130
	v_exp_f32_e32 v131, v131
	v_exp_f32_e32 v132, v132
	v_exp_f32_e32 v133, v133
	v_exp_f32_e32 v30, v30
	v_exp_f32_e32 v31, v31
	v_exp_f32_e32 v32, v32
	v_exp_f32_e32 v33, v33
	v_pk_add_f32 v[130:131], v[130:131], 1.0 op_sel_hi:[1,0]
	v_pk_add_f32 v[132:133], v[132:133], 1.0 op_sel_hi:[1,0]
	v_pk_add_f32 v[30:31], v[30:31], 1.0 op_sel_hi:[1,0]
	v_pk_add_f32 v[32:33], v[32:33], 1.0 op_sel_hi:[1,0]
	v_rcp_f32_e32 v130, v130
	v_rcp_f32_e32 v131, v131
	v_rcp_f32_e32 v132, v132
	v_rcp_f32_e32 v133, v133
	v_rcp_f32_e32 v30, v30
	v_rcp_f32_e32 v31, v31
	v_rcp_f32_e32 v32, v32
	v_rcp_f32_e32 v33, v33
	v_pk_mul_f32 v[134:135], v[134:135], v[130:131]
	v_pk_mul_f32 v[136:137], v[136:137], v[132:133]
	v_exp_f32_e32 v130, v134
	v_exp_f32_e32 v131, v135
	v_exp_f32_e32 v132, v136
	v_exp_f32_e32 v133, v137
	v_pk_mul_f32 v[246:247], v[134:135], v[226:227] op_sel_hi:[1,0]
	v_pk_mul_f32 v[248:249], v[136:137], v[226:227] op_sel_hi:[1,0]
	v_pk_fma_f32 v[250:251], v[246:247], 0.5, 1.0 op_sel_hi:[1,0,0]
	v_pk_fma_f32 v[252:253], v[248:249], 0.5, 1.0 op_sel_hi:[1,0,0]
	v_pk_mul_f32 v[250:251], v[250:251], v[246:247] neg_lo:[0,1] neg_hi:[0,1]
	v_pk_mul_f32 v[252:253], v[252:253], v[248:249] neg_lo:[0,1] neg_hi:[0,1]
	v_cmp_lt_f32_e32 vcc, s72, v246
	v_cmp_lt_f32_e64 s[12:13], s72, v247
	v_cmp_lt_f32_e64 s[14:15], s72, v248
	v_cmp_lt_f32_e64 s[16:17], s72, v249
	v_pk_fma_f32 v[246:247], v[130:131], v[130:131], 1.0 op_sel_hi:[1,1,0] neg_lo:[1,0,0] neg_hi:[1,0,0]
	v_pk_fma_f32 v[248:249], v[132:133], v[132:133], 1.0 op_sel_hi:[1,1,0] neg_lo:[1,0,0] neg_hi:[1,0,0]
	v_cndmask_b32_e32 v246, v246, v250, vcc
	v_cndmask_b32_e64 v247, v247, v251, s[12:13]
	v_cndmask_b32_e64 v248, v248, v252, s[14:15]
	v_cndmask_b32_e64 v249, v249, v253, s[16:17]
	v_sqrt_f32_e32 v246, v246
	v_sqrt_f32_e32 v247, v247
	v_sqrt_f32_e32 v248, v248
	v_sqrt_f32_e32 v249, v249
	v_pk_mul_f32 v[30:31], v[30:31], v[246:247]
	v_pk_mul_f32 v[32:33], v[32:33], v[248:249]
	v_pk_mul_f32 v[26:27], v[26:27], v[30:31]
	v_pk_mul_f32 v[28:29], v[28:29], v[32:33]
	v_cvt_pkrtz_f16_f32 v250, v134, v26
	v_cvt_pkrtz_f16_f32 v251, v135, v27
	v_cvt_pkrtz_f16_f32 v252, v136, v28
	v_cvt_pkrtz_f16_f32 v253, v137, v29
	global_store_dwordx4 v[142:143], v[250:253], off offset:-1024
	ds_read_b128 v[246:249], v208
	ds_read_b128 v[250:253], v209
	ds_read_b128 v[134:137], v210
	s_waitcnt lgkmcnt(3)
	v_pk_add_f32 v[22:23], v[22:23], v[158:159]
	v_pk_add_f32 v[24:25], v[24:25], v[160:161]
	v_pk_add_f32 v[18:19], v[18:19], v[162:163]
	v_pk_add_f32 v[20:21], v[20:21], v[164:165]
	v_pk_mul_f32 v[22:23], v[22:23], v[170:171] op_sel_hi:[1,0]
	v_pk_mul_f32 v[24:25], v[24:25], v[170:171] op_sel_hi:[1,0]
	v_pk_mul_f32 v[18:19], v[18:19], v[170:171] op_sel_hi:[1,0]
	v_pk_mul_f32 v[20:21], v[20:21], v[170:171] op_sel_hi:[1,0]
	v_exp_f32_e32 v22, v22
	v_exp_f32_e32 v23, v23
	v_exp_f32_e32 v24, v24
	v_exp_f32_e32 v25, v25
	v_exp_f32_e32 v18, v18
	v_exp_f32_e32 v19, v19
	v_exp_f32_e32 v20, v20
	v_exp_f32_e32 v21, v21
	v_pk_add_f32 v[22:23], v[22:23], 1.0 op_sel_hi:[1,0]
	v_pk_add_f32 v[24:25], v[24:25], 1.0 op_sel_hi:[1,0]
	v_pk_add_f32 v[18:19], v[18:19], 1.0 op_sel_hi:[1,0]
	v_pk_add_f32 v[20:21], v[20:21], 1.0 op_sel_hi:[1,0]
	v_rcp_f32_e32 v22, v22
	v_rcp_f32_e32 v23, v23
	v_rcp_f32_e32 v24, v24
	v_rcp_f32_e32 v25, v25
	v_rcp_f32_e32 v18, v18
	v_rcp_f32_e32 v19, v19
	v_rcp_f32_e32 v20, v20
	v_rcp_f32_e32 v21, v21
	v_pk_mul_f32 v[166:167], v[166:167], v[22:23]
	v_pk_mul_f32 v[168:169], v[168:169], v[24:25]
	v_exp_f32_e32 v22, v166
	v_exp_f32_e32 v23, v167
	v_exp_f32_e32 v24, v168
	v_exp_f32_e32 v25, v169
	v_pk_mul_f32 v[158:159], v[166:167], v[226:227] op_sel_hi:[1,0]
	v_pk_mul_f32 v[160:161], v[168:169], v[226:227] op_sel_hi:[1,0]
	v_pk_fma_f32 v[162:163], v[158:159], 0.5, 1.0 op_sel_hi:[1,0,0]
	v_pk_fma_f32 v[164:165], v[160:161], 0.5, 1.0 op_sel_hi:[1,0,0]
	v_pk_mul_f32 v[162:163], v[162:163], v[158:159] neg_lo:[0,1] neg_hi:[0,1]
	v_pk_mul_f32 v[164:165], v[164:165], v[160:161] neg_lo:[0,1] neg_hi:[0,1]
	v_cmp_lt_f32_e32 vcc, s72, v158
	v_cmp_lt_f32_e64 s[12:13], s72, v159
	v_cmp_lt_f32_e64 s[14:15], s72, v160
	v_cmp_lt_f32_e64 s[16:17], s72, v161
	v_pk_fma_f32 v[158:159], v[22:23], v[22:23], 1.0 op_sel_hi:[1,1,0] neg_lo:[1,0,0] neg_hi:[1,0,0]
	v_pk_fma_f32 v[160:161], v[24:25], v[24:25], 1.0 op_sel_hi:[1,1,0] neg_lo:[1,0,0] neg_hi:[1,0,0]
	v_cndmask_b32_e32 v158, v158, v162, vcc
	v_cndmask_b32_e64 v159, v159, v163, s[12:13]
	v_cndmask_b32_e64 v160, v160, v164, s[14:15]
	v_cndmask_b32_e64 v161, v161, v165, s[16:17]
	v_sqrt_f32_e32 v158, v158
	v_sqrt_f32_e32 v159, v159
	v_sqrt_f32_e32 v160, v160
	v_sqrt_f32_e32 v161, v161
	v_pk_mul_f32 v[18:19], v[18:19], v[158:159]
	v_pk_mul_f32 v[20:21], v[20:21], v[160:161]
	v_pk_mul_f32 v[14:15], v[14:15], v[18:19]
	v_pk_mul_f32 v[16:17], v[16:17], v[20:21]
	v_cvt_pkrtz_f16_f32 v162, v166, v14
	v_cvt_pkrtz_f16_f32 v163, v167, v15
	v_cvt_pkrtz_f16_f32 v164, v168, v16
	v_cvt_pkrtz_f16_f32 v165, v169, v17
	global_store_dwordx4 v[142:143], v[162:165], off
	s_waitcnt lgkmcnt(0)
	v_pk_add_f32 v[10:11], v[10:11], v[246:247]
	v_pk_add_f32 v[12:13], v[12:13], v[248:249]
	v_pk_add_f32 v[6:7], v[6:7], v[250:251]
	v_pk_add_f32 v[8:9], v[8:9], v[252:253]
	v_pk_mul_f32 v[10:11], v[10:11], v[170:171] op_sel_hi:[1,0]
	v_pk_mul_f32 v[12:13], v[12:13], v[170:171] op_sel_hi:[1,0]
	v_pk_mul_f32 v[6:7], v[6:7], v[170:171] op_sel_hi:[1,0]
	v_pk_mul_f32 v[8:9], v[8:9], v[170:171] op_sel_hi:[1,0]
	v_exp_f32_e32 v10, v10
	v_exp_f32_e32 v11, v11
	v_exp_f32_e32 v12, v12
	v_exp_f32_e32 v13, v13
	v_exp_f32_e32 v6, v6
	v_exp_f32_e32 v7, v7
	v_exp_f32_e32 v8, v8
	v_exp_f32_e32 v9, v9
	v_pk_add_f32 v[10:11], v[10:11], 1.0 op_sel_hi:[1,0]
	v_pk_add_f32 v[12:13], v[12:13], 1.0 op_sel_hi:[1,0]
	v_pk_add_f32 v[6:7], v[6:7], 1.0 op_sel_hi:[1,0]
	v_pk_add_f32 v[8:9], v[8:9], 1.0 op_sel_hi:[1,0]
	v_rcp_f32_e32 v10, v10
	v_rcp_f32_e32 v11, v11
	v_rcp_f32_e32 v12, v12
	v_rcp_f32_e32 v13, v13
	v_rcp_f32_e32 v6, v6
	v_rcp_f32_e32 v7, v7
	v_rcp_f32_e32 v8, v8
	v_rcp_f32_e32 v9, v9
	v_pk_mul_f32 v[134:135], v[134:135], v[10:11]
	v_pk_mul_f32 v[136:137], v[136:137], v[12:13]
	v_exp_f32_e32 v10, v134
	v_exp_f32_e32 v11, v135
	v_exp_f32_e32 v12, v136
	v_exp_f32_e32 v13, v137
	v_pk_mul_f32 v[246:247], v[134:135], v[226:227] op_sel_hi:[1,0]
	v_pk_mul_f32 v[248:249], v[136:137], v[226:227] op_sel_hi:[1,0]
	v_pk_fma_f32 v[250:251], v[246:247], 0.5, 1.0 op_sel_hi:[1,0,0]
	v_pk_fma_f32 v[252:253], v[248:249], 0.5, 1.0 op_sel_hi:[1,0,0]
	v_pk_mul_f32 v[250:251], v[250:251], v[246:247] neg_lo:[0,1] neg_hi:[0,1]
	v_pk_mul_f32 v[252:253], v[252:253], v[248:249] neg_lo:[0,1] neg_hi:[0,1]
	v_cmp_lt_f32_e32 vcc, s72, v246
	v_cmp_lt_f32_e64 s[12:13], s72, v247
	v_cmp_lt_f32_e64 s[14:15], s72, v248
	v_cmp_lt_f32_e64 s[16:17], s72, v249
	v_pk_fma_f32 v[246:247], v[10:11], v[10:11], 1.0 op_sel_hi:[1,1,0] neg_lo:[1,0,0] neg_hi:[1,0,0]
	v_pk_fma_f32 v[248:249], v[12:13], v[12:13], 1.0 op_sel_hi:[1,1,0] neg_lo:[1,0,0] neg_hi:[1,0,0]
	v_cndmask_b32_e32 v246, v246, v250, vcc
	v_cndmask_b32_e64 v247, v247, v251, s[12:13]
	v_cndmask_b32_e64 v248, v248, v252, s[14:15]
	v_cndmask_b32_e64 v249, v249, v253, s[16:17]
	v_sqrt_f32_e32 v246, v246
	v_sqrt_f32_e32 v247, v247
	v_sqrt_f32_e32 v248, v248
	v_sqrt_f32_e32 v249, v249
	v_pk_mul_f32 v[6:7], v[6:7], v[246:247]
	v_pk_mul_f32 v[8:9], v[8:9], v[248:249]
	v_pk_mul_f32 v[2:3], v[2:3], v[6:7]
	v_pk_mul_f32 v[4:5], v[4:5], v[8:9]
	v_cvt_pkrtz_f16_f32 v250, v134, v2
	v_cvt_pkrtz_f16_f32 v251, v135, v3
	v_cvt_pkrtz_f16_f32 v252, v136, v4
	v_cvt_pkrtz_f16_f32 v253, v137, v5
	global_store_dwordx4 v[142:143], v[250:253], off offset:1024
	s_and_b64 vcc, exec, s[44:45]
	s_cbranch_vccz .LBB0_341
	s_mov_b32 s10, 0x10001
	s_mov_b32 s11, 0x10001
	s_mov_b64 s[12:13], exec
	s_mov_b64 exec, s[10:11]
	v_fma_f32 v150, v172, v150, v214
	v_mul_f32_e32 v146, v146, v172
	v_fma_f32 v151, v173, v151, v215
	v_mul_f32_e32 v147, v147, v173
	v_fma_f32 v152, v174, v152, v216
	v_mul_f32_e32 v148, v148, v174
	v_fma_f32 v153, v175, v153, v217
	v_mul_f32_e32 v149, v149, v175
	v_fma_f32 v26, v176, v26, v218
	v_mul_f32_e32 v130, v130, v176
	v_fma_f32 v27, v177, v27, v219
	v_mul_f32_e32 v131, v131, v177
	v_fma_f32 v28, v178, v28, v220
	v_mul_f32_e32 v132, v132, v178
	v_fma_f32 v29, v179, v29, v221
	v_mul_f32_e32 v133, v133, v179
	v_fma_f32 v14, v180, v14, v222
	v_mul_f32_e32 v22, v22, v180
	v_fma_f32 v15, v181, v15, v223
	v_mul_f32_e32 v23, v23, v181
	v_fma_f32 v16, v182, v16, v224
	v_mul_f32_e32 v24, v24, v182
	v_fma_f32 v17, v183, v17, v225
	v_mul_f32_e32 v25, v25, v183
	v_fma_f32 v2, v192, v2, v234
	v_mul_f32_e32 v10, v10, v192
	v_fma_f32 v3, v193, v3, v235
	v_mul_f32_e32 v11, v11, v193
	v_fma_f32 v4, v194, v4, v236
	v_mul_f32_e32 v12, v12, v194
	v_fma_f32 v5, v195, v5, v237
	v_mul_f32_e32 v13, v13, v195
	s_mov_b64 exec, s[12:13]
	s_nop 4
	v_fmac_f32_dpp v150, v150, v146 row_shl:1 row_mask:0xf bank_mask:0xf bound_ctrl:1
	v_mul_f32_dpp v146, v146, v146 row_shl:1 row_mask:0xf bank_mask:0xf
	v_fmac_f32_dpp v151, v151, v147 row_shl:1 row_mask:0xf bank_mask:0xf bound_ctrl:1
	v_mul_f32_dpp v147, v147, v147 row_shl:1 row_mask:0xf bank_mask:0xf
	v_fmac_f32_dpp v152, v152, v148 row_shl:1 row_mask:0xf bank_mask:0xf bound_ctrl:1
	v_mul_f32_dpp v148, v148, v148 row_shl:1 row_mask:0xf bank_mask:0xf
	v_fmac_f32_dpp v153, v153, v149 row_shl:1 row_mask:0xf bank_mask:0xf bound_ctrl:1
	v_mul_f32_dpp v149, v149, v149 row_shl:1 row_mask:0xf bank_mask:0xf
	v_fmac_f32_dpp v26, v26, v130 row_shl:1 row_mask:0xf bank_mask:0xf bound_ctrl:1
	v_mul_f32_dpp v130, v130, v130 row_shl:1 row_mask:0xf bank_mask:0xf
	v_fmac_f32_dpp v27, v27, v131 row_shl:1 row_mask:0xf bank_mask:0xf bound_ctrl:1
	v_mul_f32_dpp v131, v131, v131 row_shl:1 row_mask:0xf bank_mask:0xf
	v_fmac_f32_dpp v28, v28, v132 row_shl:1 row_mask:0xf bank_mask:0xf bound_ctrl:1
	v_mul_f32_dpp v132, v132, v132 row_shl:1 row_mask:0xf bank_mask:0xf
	v_fmac_f32_dpp v29, v29, v133 row_shl:1 row_mask:0xf bank_mask:0xf bound_ctrl:1
	v_mul_f32_dpp v133, v133, v133 row_shl:1 row_mask:0xf bank_mask:0xf
	v_fmac_f32_dpp v14, v14, v22 row_shl:1 row_mask:0xf bank_mask:0xf bound_ctrl:1
	v_mul_f32_dpp v22, v22, v22 row_shl:1 row_mask:0xf bank_mask:0xf
	v_fmac_f32_dpp v15, v15, v23 row_shl:1 row_mask:0xf bank_mask:0xf bound_ctrl:1
	v_mul_f32_dpp v23, v23, v23 row_shl:1 row_mask:0xf bank_mask:0xf
	v_fmac_f32_dpp v16, v16, v24 row_shl:1 row_mask:0xf bank_mask:0xf bound_ctrl:1
	v_mul_f32_dpp v24, v24, v24 row_shl:1 row_mask:0xf bank_mask:0xf
	v_fmac_f32_dpp v17, v17, v25 row_shl:1 row_mask:0xf bank_mask:0xf bound_ctrl:1
	v_mul_f32_dpp v25, v25, v25 row_shl:1 row_mask:0xf bank_mask:0xf
	v_fmac_f32_dpp v2, v2, v10 row_shl:1 row_mask:0xf bank_mask:0xf bound_ctrl:1
	v_mul_f32_dpp v10, v10, v10 row_shl:1 row_mask:0xf bank_mask:0xf
	v_fmac_f32_dpp v3, v3, v11 row_shl:1 row_mask:0xf bank_mask:0xf bound_ctrl:1
	v_mul_f32_dpp v11, v11, v11 row_shl:1 row_mask:0xf bank_mask:0xf
	v_fmac_f32_dpp v4, v4, v12 row_shl:1 row_mask:0xf bank_mask:0xf bound_ctrl:1
	v_mul_f32_dpp v12, v12, v12 row_shl:1 row_mask:0xf bank_mask:0xf
	v_fmac_f32_dpp v5, v5, v13 row_shl:1 row_mask:0xf bank_mask:0xf bound_ctrl:1
	v_mul_f32_dpp v13, v13, v13 row_shl:1 row_mask:0xf bank_mask:0xf
	v_fmac_f32_dpp v150, v150, v146 row_shl:2 row_mask:0xf bank_mask:0xf bound_ctrl:1
	v_mul_f32_dpp v146, v146, v146 row_shl:2 row_mask:0xf bank_mask:0xf
	v_fmac_f32_dpp v151, v151, v147 row_shl:2 row_mask:0xf bank_mask:0xf bound_ctrl:1
	v_mul_f32_dpp v147, v147, v147 row_shl:2 row_mask:0xf bank_mask:0xf
	v_fmac_f32_dpp v152, v152, v148 row_shl:2 row_mask:0xf bank_mask:0xf bound_ctrl:1
	v_mul_f32_dpp v148, v148, v148 row_shl:2 row_mask:0xf bank_mask:0xf
	v_fmac_f32_dpp v153, v153, v149 row_shl:2 row_mask:0xf bank_mask:0xf bound_ctrl:1
	v_mul_f32_dpp v149, v149, v149 row_shl:2 row_mask:0xf bank_mask:0xf
	v_fmac_f32_dpp v26, v26, v130 row_shl:2 row_mask:0xf bank_mask:0xf bound_ctrl:1
	v_mul_f32_dpp v130, v130, v130 row_shl:2 row_mask:0xf bank_mask:0xf
	v_fmac_f32_dpp v27, v27, v131 row_shl:2 row_mask:0xf bank_mask:0xf bound_ctrl:1
	v_mul_f32_dpp v131, v131, v131 row_shl:2 row_mask:0xf bank_mask:0xf
	v_fmac_f32_dpp v28, v28, v132 row_shl:2 row_mask:0xf bank_mask:0xf bound_ctrl:1
	v_mul_f32_dpp v132, v132, v132 row_shl:2 row_mask:0xf bank_mask:0xf
	v_fmac_f32_dpp v29, v29, v133 row_shl:2 row_mask:0xf bank_mask:0xf bound_ctrl:1
	v_mul_f32_dpp v133, v133, v133 row_shl:2 row_mask:0xf bank_mask:0xf
	v_fmac_f32_dpp v14, v14, v22 row_shl:2 row_mask:0xf bank_mask:0xf bound_ctrl:1
	v_mul_f32_dpp v22, v22, v22 row_shl:2 row_mask:0xf bank_mask:0xf
	v_fmac_f32_dpp v15, v15, v23 row_shl:2 row_mask:0xf bank_mask:0xf bound_ctrl:1
	v_mul_f32_dpp v23, v23, v23 row_shl:2 row_mask:0xf bank_mask:0xf
	v_fmac_f32_dpp v16, v16, v24 row_shl:2 row_mask:0xf bank_mask:0xf bound_ctrl:1
	v_mul_f32_dpp v24, v24, v24 row_shl:2 row_mask:0xf bank_mask:0xf
	v_fmac_f32_dpp v17, v17, v25 row_shl:2 row_mask:0xf bank_mask:0xf bound_ctrl:1
	v_mul_f32_dpp v25, v25, v25 row_shl:2 row_mask:0xf bank_mask:0xf
	v_fmac_f32_dpp v2, v2, v10 row_shl:2 row_mask:0xf bank_mask:0xf bound_ctrl:1
	v_mul_f32_dpp v10, v10, v10 row_shl:2 row_mask:0xf bank_mask:0xf
	v_fmac_f32_dpp v3, v3, v11 row_shl:2 row_mask:0xf bank_mask:0xf bound_ctrl:1
	v_mul_f32_dpp v11, v11, v11 row_shl:2 row_mask:0xf bank_mask:0xf
	v_fmac_f32_dpp v4, v4, v12 row_shl:2 row_mask:0xf bank_mask:0xf bound_ctrl:1
	v_mul_f32_dpp v12, v12, v12 row_shl:2 row_mask:0xf bank_mask:0xf
	v_fmac_f32_dpp v5, v5, v13 row_shl:2 row_mask:0xf bank_mask:0xf bound_ctrl:1
	v_mul_f32_dpp v13, v13, v13 row_shl:2 row_mask:0xf bank_mask:0xf
	v_fmac_f32_dpp v150, v150, v146 row_shl:4 row_mask:0xf bank_mask:0xf bound_ctrl:1
	v_mul_f32_dpp v146, v146, v146 row_shl:4 row_mask:0xf bank_mask:0xf
	v_fmac_f32_dpp v151, v151, v147 row_shl:4 row_mask:0xf bank_mask:0xf bound_ctrl:1
	v_mul_f32_dpp v147, v147, v147 row_shl:4 row_mask:0xf bank_mask:0xf
	v_fmac_f32_dpp v152, v152, v148 row_shl:4 row_mask:0xf bank_mask:0xf bound_ctrl:1
	v_mul_f32_dpp v148, v148, v148 row_shl:4 row_mask:0xf bank_mask:0xf
	v_fmac_f32_dpp v153, v153, v149 row_shl:4 row_mask:0xf bank_mask:0xf bound_ctrl:1
	v_mul_f32_dpp v149, v149, v149 row_shl:4 row_mask:0xf bank_mask:0xf
	v_fmac_f32_dpp v26, v26, v130 row_shl:4 row_mask:0xf bank_mask:0xf bound_ctrl:1
	v_mul_f32_dpp v130, v130, v130 row_shl:4 row_mask:0xf bank_mask:0xf
	v_fmac_f32_dpp v27, v27, v131 row_shl:4 row_mask:0xf bank_mask:0xf bound_ctrl:1
	v_mul_f32_dpp v131, v131, v131 row_shl:4 row_mask:0xf bank_mask:0xf
	v_fmac_f32_dpp v28, v28, v132 row_shl:4 row_mask:0xf bank_mask:0xf bound_ctrl:1
	v_mul_f32_dpp v132, v132, v132 row_shl:4 row_mask:0xf bank_mask:0xf
	v_fmac_f32_dpp v29, v29, v133 row_shl:4 row_mask:0xf bank_mask:0xf bound_ctrl:1
	v_mul_f32_dpp v133, v133, v133 row_shl:4 row_mask:0xf bank_mask:0xf
	v_fmac_f32_dpp v14, v14, v22 row_shl:4 row_mask:0xf bank_mask:0xf bound_ctrl:1
	v_mul_f32_dpp v22, v22, v22 row_shl:4 row_mask:0xf bank_mask:0xf
	v_fmac_f32_dpp v15, v15, v23 row_shl:4 row_mask:0xf bank_mask:0xf bound_ctrl:1
	v_mul_f32_dpp v23, v23, v23 row_shl:4 row_mask:0xf bank_mask:0xf
	v_fmac_f32_dpp v16, v16, v24 row_shl:4 row_mask:0xf bank_mask:0xf bound_ctrl:1
	v_mul_f32_dpp v24, v24, v24 row_shl:4 row_mask:0xf bank_mask:0xf
	v_fmac_f32_dpp v17, v17, v25 row_shl:4 row_mask:0xf bank_mask:0xf bound_ctrl:1
	v_mul_f32_dpp v25, v25, v25 row_shl:4 row_mask:0xf bank_mask:0xf
	v_fmac_f32_dpp v2, v2, v10 row_shl:4 row_mask:0xf bank_mask:0xf bound_ctrl:1
	v_mul_f32_dpp v10, v10, v10 row_shl:4 row_mask:0xf bank_mask:0xf
	v_fmac_f32_dpp v3, v3, v11 row_shl:4 row_mask:0xf bank_mask:0xf bound_ctrl:1
	v_mul_f32_dpp v11, v11, v11 row_shl:4 row_mask:0xf bank_mask:0xf
	v_fmac_f32_dpp v4, v4, v12 row_shl:4 row_mask:0xf bank_mask:0xf bound_ctrl:1
	v_mul_f32_dpp v12, v12, v12 row_shl:4 row_mask:0xf bank_mask:0xf
	v_fmac_f32_dpp v5, v5, v13 row_shl:4 row_mask:0xf bank_mask:0xf bound_ctrl:1
	v_mul_f32_dpp v13, v13, v13 row_shl:4 row_mask:0xf bank_mask:0xf
	v_fmac_f32_dpp v150, v150, v146 row_shl:8 row_mask:0xf bank_mask:0xf bound_ctrl:1
	v_mul_f32_dpp v146, v146, v146 row_shl:8 row_mask:0xf bank_mask:0xf
	v_fmac_f32_dpp v151, v151, v147 row_shl:8 row_mask:0xf bank_mask:0xf bound_ctrl:1
	v_mul_f32_dpp v147, v147, v147 row_shl:8 row_mask:0xf bank_mask:0xf
	v_fmac_f32_dpp v152, v152, v148 row_shl:8 row_mask:0xf bank_mask:0xf bound_ctrl:1
	v_mul_f32_dpp v148, v148, v148 row_shl:8 row_mask:0xf bank_mask:0xf
	v_fmac_f32_dpp v153, v153, v149 row_shl:8 row_mask:0xf bank_mask:0xf bound_ctrl:1
	v_mul_f32_dpp v149, v149, v149 row_shl:8 row_mask:0xf bank_mask:0xf
	v_fmac_f32_dpp v26, v26, v130 row_shl:8 row_mask:0xf bank_mask:0xf bound_ctrl:1
	v_mul_f32_dpp v130, v130, v130 row_shl:8 row_mask:0xf bank_mask:0xf
	v_fmac_f32_dpp v27, v27, v131 row_shl:8 row_mask:0xf bank_mask:0xf bound_ctrl:1
	v_mul_f32_dpp v131, v131, v131 row_shl:8 row_mask:0xf bank_mask:0xf
	v_fmac_f32_dpp v28, v28, v132 row_shl:8 row_mask:0xf bank_mask:0xf bound_ctrl:1
	v_mul_f32_dpp v132, v132, v132 row_shl:8 row_mask:0xf bank_mask:0xf
	v_fmac_f32_dpp v29, v29, v133 row_shl:8 row_mask:0xf bank_mask:0xf bound_ctrl:1
	v_mul_f32_dpp v133, v133, v133 row_shl:8 row_mask:0xf bank_mask:0xf
	v_fmac_f32_dpp v14, v14, v22 row_shl:8 row_mask:0xf bank_mask:0xf bound_ctrl:1
	v_mul_f32_dpp v22, v22, v22 row_shl:8 row_mask:0xf bank_mask:0xf
	v_fmac_f32_dpp v15, v15, v23 row_shl:8 row_mask:0xf bank_mask:0xf bound_ctrl:1
	v_mul_f32_dpp v23, v23, v23 row_shl:8 row_mask:0xf bank_mask:0xf
	v_fmac_f32_dpp v16, v16, v24 row_shl:8 row_mask:0xf bank_mask:0xf bound_ctrl:1
	v_mul_f32_dpp v24, v24, v24 row_shl:8 row_mask:0xf bank_mask:0xf
	v_fmac_f32_dpp v17, v17, v25 row_shl:8 row_mask:0xf bank_mask:0xf bound_ctrl:1
	v_mul_f32_dpp v25, v25, v25 row_shl:8 row_mask:0xf bank_mask:0xf
	v_fmac_f32_dpp v2, v2, v10 row_shl:8 row_mask:0xf bank_mask:0xf bound_ctrl:1
	v_mul_f32_dpp v10, v10, v10 row_shl:8 row_mask:0xf bank_mask:0xf
	v_fmac_f32_dpp v3, v3, v11 row_shl:8 row_mask:0xf bank_mask:0xf bound_ctrl:1
	v_mul_f32_dpp v11, v11, v11 row_shl:8 row_mask:0xf bank_mask:0xf
	v_fmac_f32_dpp v4, v4, v12 row_shl:8 row_mask:0xf bank_mask:0xf bound_ctrl:1
	v_mul_f32_dpp v12, v12, v12 row_shl:8 row_mask:0xf bank_mask:0xf
	v_fmac_f32_dpp v5, v5, v13 row_shl:8 row_mask:0xf bank_mask:0xf bound_ctrl:1
	v_mul_f32_dpp v13, v13, v13 row_shl:8 row_mask:0xf bank_mask:0xf
	v_mov_b64_e32 v[172:173], v[146:147]
	v_mov_b64_e32 v[214:215], v[150:151]
	v_mov_b64_e32 v[174:175], v[148:149]
	v_mov_b64_e32 v[216:217], v[152:153]
	v_mov_b64_e32 v[176:177], v[130:131]
	v_mov_b64_e32 v[218:219], v[26:27]
	v_mov_b64_e32 v[178:179], v[132:133]
	v_mov_b64_e32 v[220:221], v[28:29]
	v_mov_b64_e32 v[180:181], v[22:23]
	v_mov_b64_e32 v[222:223], v[14:15]
	v_mov_b64_e32 v[182:183], v[24:25]
	v_mov_b64_e32 v[224:225], v[16:17]
	v_mov_b64_e32 v[192:193], v[10:11]
	v_mov_b64_e32 v[234:235], v[2:3]
	v_mov_b64_e32 v[194:195], v[12:13]
	v_mov_b64_e32 v[236:237], v[4:5]
	s_mov_b64 s[10:11], 0
.LBB0_341:
	s_andn2_b64 vcc, exec, s[10:11]
	s_cbranch_vccnz .LBB0_338
	v_fmac_f32_dpp v150, v214, v146 row_shl:15 row_mask:0xf bank_mask:0xf bound_ctrl:1
	v_mul_f32_dpp v146, v172, v146 row_shl:15 row_mask:0xf bank_mask:0xf
	v_fmac_f32_dpp v151, v215, v147 row_shl:15 row_mask:0xf bank_mask:0xf bound_ctrl:1
	v_mul_f32_dpp v147, v173, v147 row_shl:15 row_mask:0xf bank_mask:0xf
	v_fmac_f32_dpp v152, v216, v148 row_shl:15 row_mask:0xf bank_mask:0xf bound_ctrl:1
	v_mul_f32_dpp v148, v174, v148 row_shl:15 row_mask:0xf bank_mask:0xf
	v_fmac_f32_dpp v153, v217, v149 row_shl:15 row_mask:0xf bank_mask:0xf bound_ctrl:1
	v_mul_f32_dpp v149, v175, v149 row_shl:15 row_mask:0xf bank_mask:0xf
	v_fmac_f32_dpp v26, v218, v130 row_shl:15 row_mask:0xf bank_mask:0xf bound_ctrl:1
	v_mul_f32_dpp v130, v176, v130 row_shl:15 row_mask:0xf bank_mask:0xf
	v_fmac_f32_dpp v27, v219, v131 row_shl:15 row_mask:0xf bank_mask:0xf bound_ctrl:1
	v_mul_f32_dpp v131, v177, v131 row_shl:15 row_mask:0xf bank_mask:0xf
	v_fmac_f32_dpp v28, v220, v132 row_shl:15 row_mask:0xf bank_mask:0xf bound_ctrl:1
	v_mul_f32_dpp v132, v178, v132 row_shl:15 row_mask:0xf bank_mask:0xf
	v_fmac_f32_dpp v29, v221, v133 row_shl:15 row_mask:0xf bank_mask:0xf bound_ctrl:1
	v_mul_f32_dpp v133, v179, v133 row_shl:15 row_mask:0xf bank_mask:0xf
	v_fmac_f32_dpp v14, v222, v22 row_shl:15 row_mask:0xf bank_mask:0xf bound_ctrl:1
	v_mul_f32_dpp v22, v180, v22 row_shl:15 row_mask:0xf bank_mask:0xf
	v_fmac_f32_dpp v15, v223, v23 row_shl:15 row_mask:0xf bank_mask:0xf bound_ctrl:1
	v_mul_f32_dpp v23, v181, v23 row_shl:15 row_mask:0xf bank_mask:0xf
	v_fmac_f32_dpp v16, v224, v24 row_shl:15 row_mask:0xf bank_mask:0xf bound_ctrl:1
	v_mul_f32_dpp v24, v182, v24 row_shl:15 row_mask:0xf bank_mask:0xf
	v_fmac_f32_dpp v17, v225, v25 row_shl:15 row_mask:0xf bank_mask:0xf bound_ctrl:1
	v_mul_f32_dpp v25, v183, v25 row_shl:15 row_mask:0xf bank_mask:0xf
	v_fmac_f32_dpp v2, v234, v10 row_shl:15 row_mask:0xf bank_mask:0xf bound_ctrl:1
	v_mul_f32_dpp v10, v192, v10 row_shl:15 row_mask:0xf bank_mask:0xf
	v_fmac_f32_dpp v3, v235, v11 row_shl:15 row_mask:0xf bank_mask:0xf bound_ctrl:1
	v_mul_f32_dpp v11, v193, v11 row_shl:15 row_mask:0xf bank_mask:0xf
	v_fmac_f32_dpp v4, v236, v12 row_shl:15 row_mask:0xf bank_mask:0xf bound_ctrl:1
	v_mul_f32_dpp v12, v194, v12 row_shl:15 row_mask:0xf bank_mask:0xf
	v_fmac_f32_dpp v5, v237, v13 row_shl:15 row_mask:0xf bank_mask:0xf bound_ctrl:1
	v_mul_f32_dpp v13, v195, v13 row_shl:15 row_mask:0xf bank_mask:0xf
	v_fmac_f32_dpp v150, v150, v146 row_shr:1 row_mask:0xf bank_mask:0xf bound_ctrl:1
	v_mul_f32_dpp v146, v146, v146 row_shr:1 row_mask:0xf bank_mask:0xf
	v_fmac_f32_dpp v151, v151, v147 row_shr:1 row_mask:0xf bank_mask:0xf bound_ctrl:1
	v_mul_f32_dpp v147, v147, v147 row_shr:1 row_mask:0xf bank_mask:0xf
	v_fmac_f32_dpp v152, v152, v148 row_shr:1 row_mask:0xf bank_mask:0xf bound_ctrl:1
	v_mul_f32_dpp v148, v148, v148 row_shr:1 row_mask:0xf bank_mask:0xf
	v_fmac_f32_dpp v153, v153, v149 row_shr:1 row_mask:0xf bank_mask:0xf bound_ctrl:1
	v_mul_f32_dpp v149, v149, v149 row_shr:1 row_mask:0xf bank_mask:0xf
	v_fmac_f32_dpp v26, v26, v130 row_shr:1 row_mask:0xf bank_mask:0xf bound_ctrl:1
	v_mul_f32_dpp v130, v130, v130 row_shr:1 row_mask:0xf bank_mask:0xf
	v_fmac_f32_dpp v27, v27, v131 row_shr:1 row_mask:0xf bank_mask:0xf bound_ctrl:1
	v_mul_f32_dpp v131, v131, v131 row_shr:1 row_mask:0xf bank_mask:0xf
	v_fmac_f32_dpp v28, v28, v132 row_shr:1 row_mask:0xf bank_mask:0xf bound_ctrl:1
	v_mul_f32_dpp v132, v132, v132 row_shr:1 row_mask:0xf bank_mask:0xf
	v_fmac_f32_dpp v29, v29, v133 row_shr:1 row_mask:0xf bank_mask:0xf bound_ctrl:1
	v_mul_f32_dpp v133, v133, v133 row_shr:1 row_mask:0xf bank_mask:0xf
	v_fmac_f32_dpp v14, v14, v22 row_shr:1 row_mask:0xf bank_mask:0xf bound_ctrl:1
	v_mul_f32_dpp v22, v22, v22 row_shr:1 row_mask:0xf bank_mask:0xf
	v_fmac_f32_dpp v15, v15, v23 row_shr:1 row_mask:0xf bank_mask:0xf bound_ctrl:1
	v_mul_f32_dpp v23, v23, v23 row_shr:1 row_mask:0xf bank_mask:0xf
	v_fmac_f32_dpp v16, v16, v24 row_shr:1 row_mask:0xf bank_mask:0xf bound_ctrl:1
	v_mul_f32_dpp v24, v24, v24 row_shr:1 row_mask:0xf bank_mask:0xf
	v_fmac_f32_dpp v17, v17, v25 row_shr:1 row_mask:0xf bank_mask:0xf bound_ctrl:1
	v_mul_f32_dpp v25, v25, v25 row_shr:1 row_mask:0xf bank_mask:0xf
	v_fmac_f32_dpp v2, v2, v10 row_shr:1 row_mask:0xf bank_mask:0xf bound_ctrl:1
	v_mul_f32_dpp v10, v10, v10 row_shr:1 row_mask:0xf bank_mask:0xf
	v_fmac_f32_dpp v3, v3, v11 row_shr:1 row_mask:0xf bank_mask:0xf bound_ctrl:1
	v_mul_f32_dpp v11, v11, v11 row_shr:1 row_mask:0xf bank_mask:0xf
	v_fmac_f32_dpp v4, v4, v12 row_shr:1 row_mask:0xf bank_mask:0xf bound_ctrl:1
	v_mul_f32_dpp v12, v12, v12 row_shr:1 row_mask:0xf bank_mask:0xf
	v_fmac_f32_dpp v5, v5, v13 row_shr:1 row_mask:0xf bank_mask:0xf bound_ctrl:1
	v_mul_f32_dpp v13, v13, v13 row_shr:1 row_mask:0xf bank_mask:0xf
	v_fmac_f32_dpp v150, v150, v146 row_shr:2 row_mask:0xf bank_mask:0xf bound_ctrl:1
	v_mul_f32_dpp v146, v146, v146 row_shr:2 row_mask:0xf bank_mask:0xf
	v_fmac_f32_dpp v151, v151, v147 row_shr:2 row_mask:0xf bank_mask:0xf bound_ctrl:1
	v_mul_f32_dpp v147, v147, v147 row_shr:2 row_mask:0xf bank_mask:0xf
	v_fmac_f32_dpp v152, v152, v148 row_shr:2 row_mask:0xf bank_mask:0xf bound_ctrl:1
	v_mul_f32_dpp v148, v148, v148 row_shr:2 row_mask:0xf bank_mask:0xf
	v_fmac_f32_dpp v153, v153, v149 row_shr:2 row_mask:0xf bank_mask:0xf bound_ctrl:1
	v_mul_f32_dpp v149, v149, v149 row_shr:2 row_mask:0xf bank_mask:0xf
	v_fmac_f32_dpp v26, v26, v130 row_shr:2 row_mask:0xf bank_mask:0xf bound_ctrl:1
	v_mul_f32_dpp v130, v130, v130 row_shr:2 row_mask:0xf bank_mask:0xf
	v_fmac_f32_dpp v27, v27, v131 row_shr:2 row_mask:0xf bank_mask:0xf bound_ctrl:1
	v_mul_f32_dpp v131, v131, v131 row_shr:2 row_mask:0xf bank_mask:0xf
	v_fmac_f32_dpp v28, v28, v132 row_shr:2 row_mask:0xf bank_mask:0xf bound_ctrl:1
	v_mul_f32_dpp v132, v132, v132 row_shr:2 row_mask:0xf bank_mask:0xf
	v_fmac_f32_dpp v29, v29, v133 row_shr:2 row_mask:0xf bank_mask:0xf bound_ctrl:1
	v_mul_f32_dpp v133, v133, v133 row_shr:2 row_mask:0xf bank_mask:0xf
	v_fmac_f32_dpp v14, v14, v22 row_shr:2 row_mask:0xf bank_mask:0xf bound_ctrl:1
	v_mul_f32_dpp v22, v22, v22 row_shr:2 row_mask:0xf bank_mask:0xf
	v_fmac_f32_dpp v15, v15, v23 row_shr:2 row_mask:0xf bank_mask:0xf bound_ctrl:1
	v_mul_f32_dpp v23, v23, v23 row_shr:2 row_mask:0xf bank_mask:0xf
	v_fmac_f32_dpp v16, v16, v24 row_shr:2 row_mask:0xf bank_mask:0xf bound_ctrl:1
	v_mul_f32_dpp v24, v24, v24 row_shr:2 row_mask:0xf bank_mask:0xf
	v_fmac_f32_dpp v17, v17, v25 row_shr:2 row_mask:0xf bank_mask:0xf bound_ctrl:1
	v_mul_f32_dpp v25, v25, v25 row_shr:2 row_mask:0xf bank_mask:0xf
	v_fmac_f32_dpp v2, v2, v10 row_shr:2 row_mask:0xf bank_mask:0xf bound_ctrl:1
	v_mul_f32_dpp v10, v10, v10 row_shr:2 row_mask:0xf bank_mask:0xf
	v_fmac_f32_dpp v3, v3, v11 row_shr:2 row_mask:0xf bank_mask:0xf bound_ctrl:1
	v_mul_f32_dpp v11, v11, v11 row_shr:2 row_mask:0xf bank_mask:0xf
	v_fmac_f32_dpp v4, v4, v12 row_shr:2 row_mask:0xf bank_mask:0xf bound_ctrl:1
	v_mul_f32_dpp v12, v12, v12 row_shr:2 row_mask:0xf bank_mask:0xf
	v_fmac_f32_dpp v5, v5, v13 row_shr:2 row_mask:0xf bank_mask:0xf bound_ctrl:1
	v_mul_f32_dpp v13, v13, v13 row_shr:2 row_mask:0xf bank_mask:0xf
	v_fmac_f32_dpp v150, v150, v146 row_shr:4 row_mask:0xf bank_mask:0xf bound_ctrl:1
	v_mul_f32_dpp v146, v146, v146 row_shr:4 row_mask:0xf bank_mask:0xf
	v_fmac_f32_dpp v151, v151, v147 row_shr:4 row_mask:0xf bank_mask:0xf bound_ctrl:1
	v_mul_f32_dpp v147, v147, v147 row_shr:4 row_mask:0xf bank_mask:0xf
	v_fmac_f32_dpp v152, v152, v148 row_shr:4 row_mask:0xf bank_mask:0xf bound_ctrl:1
	v_mul_f32_dpp v148, v148, v148 row_shr:4 row_mask:0xf bank_mask:0xf
	v_fmac_f32_dpp v153, v153, v149 row_shr:4 row_mask:0xf bank_mask:0xf bound_ctrl:1
	v_mul_f32_dpp v149, v149, v149 row_shr:4 row_mask:0xf bank_mask:0xf
	v_fmac_f32_dpp v26, v26, v130 row_shr:4 row_mask:0xf bank_mask:0xf bound_ctrl:1
	v_mul_f32_dpp v130, v130, v130 row_shr:4 row_mask:0xf bank_mask:0xf
	v_fmac_f32_dpp v27, v27, v131 row_shr:4 row_mask:0xf bank_mask:0xf bound_ctrl:1
	v_mul_f32_dpp v131, v131, v131 row_shr:4 row_mask:0xf bank_mask:0xf
	v_fmac_f32_dpp v28, v28, v132 row_shr:4 row_mask:0xf bank_mask:0xf bound_ctrl:1
	v_mul_f32_dpp v132, v132, v132 row_shr:4 row_mask:0xf bank_mask:0xf
	v_fmac_f32_dpp v29, v29, v133 row_shr:4 row_mask:0xf bank_mask:0xf bound_ctrl:1
	v_mul_f32_dpp v133, v133, v133 row_shr:4 row_mask:0xf bank_mask:0xf
	v_fmac_f32_dpp v14, v14, v22 row_shr:4 row_mask:0xf bank_mask:0xf bound_ctrl:1
	v_mul_f32_dpp v22, v22, v22 row_shr:4 row_mask:0xf bank_mask:0xf
	v_fmac_f32_dpp v15, v15, v23 row_shr:4 row_mask:0xf bank_mask:0xf bound_ctrl:1
	v_mul_f32_dpp v23, v23, v23 row_shr:4 row_mask:0xf bank_mask:0xf
	v_fmac_f32_dpp v16, v16, v24 row_shr:4 row_mask:0xf bank_mask:0xf bound_ctrl:1
	v_mul_f32_dpp v24, v24, v24 row_shr:4 row_mask:0xf bank_mask:0xf
	v_fmac_f32_dpp v17, v17, v25 row_shr:4 row_mask:0xf bank_mask:0xf bound_ctrl:1
	v_mul_f32_dpp v25, v25, v25 row_shr:4 row_mask:0xf bank_mask:0xf
	v_fmac_f32_dpp v2, v2, v10 row_shr:4 row_mask:0xf bank_mask:0xf bound_ctrl:1
	v_mul_f32_dpp v10, v10, v10 row_shr:4 row_mask:0xf bank_mask:0xf
	v_fmac_f32_dpp v3, v3, v11 row_shr:4 row_mask:0xf bank_mask:0xf bound_ctrl:1
	v_mul_f32_dpp v11, v11, v11 row_shr:4 row_mask:0xf bank_mask:0xf
	v_fmac_f32_dpp v4, v4, v12 row_shr:4 row_mask:0xf bank_mask:0xf bound_ctrl:1
	v_mul_f32_dpp v12, v12, v12 row_shr:4 row_mask:0xf bank_mask:0xf
	v_fmac_f32_dpp v5, v5, v13 row_shr:4 row_mask:0xf bank_mask:0xf bound_ctrl:1
	v_mul_f32_dpp v13, v13, v13 row_shr:4 row_mask:0xf bank_mask:0xf
	v_fmac_f32_dpp v150, v150, v146 row_shr:8 row_mask:0xf bank_mask:0xf bound_ctrl:1
	v_mul_f32_dpp v146, v146, v146 row_shr:8 row_mask:0xf bank_mask:0xf
	v_fmac_f32_dpp v151, v151, v147 row_shr:8 row_mask:0xf bank_mask:0xf bound_ctrl:1
	v_mul_f32_dpp v147, v147, v147 row_shr:8 row_mask:0xf bank_mask:0xf
	v_fmac_f32_dpp v152, v152, v148 row_shr:8 row_mask:0xf bank_mask:0xf bound_ctrl:1
	v_mul_f32_dpp v148, v148, v148 row_shr:8 row_mask:0xf bank_mask:0xf
	v_fmac_f32_dpp v153, v153, v149 row_shr:8 row_mask:0xf bank_mask:0xf bound_ctrl:1
	v_mul_f32_dpp v149, v149, v149 row_shr:8 row_mask:0xf bank_mask:0xf
	v_fmac_f32_dpp v26, v26, v130 row_shr:8 row_mask:0xf bank_mask:0xf bound_ctrl:1
	v_mul_f32_dpp v130, v130, v130 row_shr:8 row_mask:0xf bank_mask:0xf
	v_fmac_f32_dpp v27, v27, v131 row_shr:8 row_mask:0xf bank_mask:0xf bound_ctrl:1
	v_mul_f32_dpp v131, v131, v131 row_shr:8 row_mask:0xf bank_mask:0xf
	v_fmac_f32_dpp v28, v28, v132 row_shr:8 row_mask:0xf bank_mask:0xf bound_ctrl:1
	v_mul_f32_dpp v132, v132, v132 row_shr:8 row_mask:0xf bank_mask:0xf
	v_fmac_f32_dpp v29, v29, v133 row_shr:8 row_mask:0xf bank_mask:0xf bound_ctrl:1
	v_mul_f32_dpp v133, v133, v133 row_shr:8 row_mask:0xf bank_mask:0xf
	v_fmac_f32_dpp v14, v14, v22 row_shr:8 row_mask:0xf bank_mask:0xf bound_ctrl:1
	v_mul_f32_dpp v22, v22, v22 row_shr:8 row_mask:0xf bank_mask:0xf
	v_fmac_f32_dpp v15, v15, v23 row_shr:8 row_mask:0xf bank_mask:0xf bound_ctrl:1
	v_mul_f32_dpp v23, v23, v23 row_shr:8 row_mask:0xf bank_mask:0xf
	v_fmac_f32_dpp v16, v16, v24 row_shr:8 row_mask:0xf bank_mask:0xf bound_ctrl:1
	v_mul_f32_dpp v24, v24, v24 row_shr:8 row_mask:0xf bank_mask:0xf
	v_fmac_f32_dpp v17, v17, v25 row_shr:8 row_mask:0xf bank_mask:0xf bound_ctrl:1
	v_mul_f32_dpp v25, v25, v25 row_shr:8 row_mask:0xf bank_mask:0xf
	v_fmac_f32_dpp v2, v2, v10 row_shr:8 row_mask:0xf bank_mask:0xf bound_ctrl:1
	v_mul_f32_dpp v10, v10, v10 row_shr:8 row_mask:0xf bank_mask:0xf
	v_fmac_f32_dpp v3, v3, v11 row_shr:8 row_mask:0xf bank_mask:0xf bound_ctrl:1
	v_mul_f32_dpp v11, v11, v11 row_shr:8 row_mask:0xf bank_mask:0xf
	v_fmac_f32_dpp v4, v4, v12 row_shr:8 row_mask:0xf bank_mask:0xf bound_ctrl:1
	v_mul_f32_dpp v12, v12, v12 row_shr:8 row_mask:0xf bank_mask:0xf
	v_fmac_f32_dpp v5, v5, v13 row_shr:8 row_mask:0xf bank_mask:0xf bound_ctrl:1
	v_mul_f32_dpp v13, v13, v13 row_shr:8 row_mask:0xf bank_mask:0xf
	v_mov_b64_e32 v[172:173], v[146:147]
	v_mov_b64_e32 v[214:215], v[150:151]
	v_mov_b64_e32 v[174:175], v[148:149]
	v_mov_b64_e32 v[216:217], v[152:153]
	v_mov_b64_e32 v[176:177], v[130:131]
	v_mov_b64_e32 v[218:219], v[26:27]
	v_mov_b64_e32 v[178:179], v[132:133]
	v_mov_b64_e32 v[220:221], v[28:29]
	v_mov_b64_e32 v[180:181], v[22:23]
	v_mov_b64_e32 v[222:223], v[14:15]
	v_mov_b64_e32 v[182:183], v[24:25]
	v_mov_b64_e32 v[224:225], v[16:17]
	v_mov_b64_e32 v[192:193], v[10:11]
	v_mov_b64_e32 v[234:235], v[2:3]
	v_mov_b64_e32 v[194:195], v[12:13]
	v_mov_b64_e32 v[236:237], v[4:5]
	s_branch .LBB0_338
